# F3: odd workgroups run filter_gen before norm+convert (compute-bound and bandwidth-bound parts overlap across workgroups)
# speedup vs baseline: 1.0038x; 1.0003x over previous
; #define LAS __attribute__((address_space(3)))
; DI int opaque_tid(int wave) { int t = wave * 64 + (int)__builtin_amdgcn_mbcnt_hi(~0u, __builtin_amdgcn_mbcnt_lo(~0u, 0u)); asm volatile("" : "+v"(t)); return t; }
; DI unsigned xb_add(unsigned* p, unsigned v) { return __hip_atomic_fetch_add(p, v, __ATOMIC_RELAXED, __HIP_MEMORY_SCOPE_AGENT); }
; DI unsigned xb_xcc_id() { return (unsigned)__builtin_amdgcn_s_getreg((3 << 11) | 20) & 0xFu; }
; __global__ void __launch_bounds__(512, 2) mega(Args args) {
;     ...
;     const int G0 = gridDim.x, bx0 = blockIdx.x, wave0 = __builtin_amdgcn_readfirstlane(threadIdx.x >> 6);
;     const int vcu0 = (G0 % 8 == 0) ? (bx0 % 8) * (G0 / 8) + bx0 / 8 : bx0;
;     const int lo = args.ph_lo, hi = args.ph_hi; int ph = 0;
;     { const int t0 = opaque_tid(wave0);
;       if (t0 < 2) ((volatile LAS unsigned*)(lds + LDS_ST))[t0] = 0u;
;       __syncthreads();
;       if (t0 == 0) (void)xb_add(&((unsigned*)args.ws)[XB_XCNT(xb_xcc_id())], 1u); }
.LBB0_2:
	s_mov_b32 s0, 0
	v_writelane_b32 v255, s0, 59
	s_load_dwordx2 s[0:1], s[84:85], 0xf8
	v_mbcnt_lo_u32_b32 v2, -1, 0
	v_mbcnt_hi_u32_b32 v249, -1, v2
	s_waitcnt lgkmcnt(0)
	v_writelane_b32 v255, s0, 1
	s_nop 1
	v_writelane_b32 v255, s1, 2
	s_and_b32 s0, s4, 0xffffffc0
	v_add_u32_e32 v213, s0, v249
	v_mov_b32_e32 v2, v213
	s_nop 0
	v_cmp_gt_i32_e32 vcc, 2, v2
	s_and_saveexec_b64 s[0:1], vcc
	v_lshl_add_u32 v3, v2, 2, 0
	v_add_u32_e32 v3, 0x23fc0, v3
	v_mov_b32_e32 v4, 0
	ds_write_b32 v3, v4
	s_or_b64 exec, exec, s[0:1]
	v_cmp_eq_u32_e32 vcc, 0, v2
	s_waitcnt lgkmcnt(0)
	s_barrier
	s_and_saveexec_b64 s[0:1], vcc
	s_cbranch_execz .LBB0_7
	s_mov_b64 s[2:3], exec
	v_mbcnt_lo_u32_b32 v2, s2, 0
	v_mbcnt_hi_u32_b32 v2, s3, v2
	v_cmp_eq_u32_e32 vcc, 0, v2
	s_getreg_b32 s5, hwreg(HW_REG_XCC_ID, 0, 4)
	s_and_b64 s[6:7], exec, vcc
	s_mov_b64 exec, s[6:7]
	s_cbranch_execz .LBB0_7
	s_load_dwordx2 s[6:7], s[84:85], 0xf0
	s_lshl_b32 s5, s5, 8
	s_and_b32 s5, s5, 0xf00
	s_bcnt1_i32_b64 s2, s[2:3]
	v_mov_b32_e32 v2, s5
	v_mov_b32_e32 v3, s2
	s_waitcnt lgkmcnt(0)
	global_atomic_add v2, v3, s[6:7] offset:1024

; DI float bflo(unsigned w) { return __uint_as_float(w << 16); }
; DI float bfhi(unsigned w) { return __uint_as_float(w & 0xffff0000u); }
; template <bool XOUT_BF, int NR>
; DI void norm_rows(const bf16_t* xin, const bf16_t* Rb, const float* gpost, void* xout, const float* gpre, bf16_t* xnb, size_t row0, size_t rstride, int lane) {
;     f32x4 v[NR][4], r[NR][4];
; #pragma unroll
;     for (int q = 0; q < NR; ++q)
; #pragma unroll
;         for (int j = 0; j < 4; ++j) { const size_t off = (row0 + q * rstride) * D + 4 * lane + 256 * j;
;             const u32x2 w = __builtin_nontemporal_load((const u32x2*)(xin + off)); v[q][j] = (f32x4){bflo(w.x), bfhi(w.x), bflo(w.y), bfhi(w.y)};
;             const u32x2 w2 = __builtin_nontemporal_load((const u32x2*)(Rb + off)); r[q][j] = (f32x4){bflo(w2.x), bfhi(w2.x), bflo(w2.y), bfhi(w2.y)}; }
; __global__ void __launch_bounds__(512, 2) mega(Args args) {
;     ...
;         PH_BEGIN
;             const bool more = l + 1 < DEPTH;
;             if (more) { for (int m = gw; m < TT; m += 4 * NGW) norm_rows<true, 4>(XB, R, in.g_ff_post + l * D, XB, in.g_mix_pre + (l + 1) * D, XN, (size_t)m, (size_t)NGW, lane); }
;             else { for (int m = gw; m < TT; m += 4 * NGW) norm_rows<false, 4>(XB, R, in.g_ff_post + l * D, xo, nullptr, nullptr, (size_t)m, (size_t)NGW, lane); }
;             if (more) { convert_weights(in, l + 1, ws, lds, gw, NGW, wave, lane); filter_gen(in, l + 1, ws, lds, vcu, G, wave, tid); }
.Lf3_pro:
	s_mov_b64 s[4:5], s[84:85]
	s_load_dwordx2 s[46:47], s[4:5], 0x30
	s_load_dwordx8 s[8:15], s[4:5], 0x40
	s_load_dwordx2 s[6:7], s[4:5], 0x60
	s_load_dwordx4 s[28:31], s[4:5], 0x88
	s_load_dwordx2 s[40:41], s[4:5], 0xc0
	s_load_dwordx4 s[24:27], s[4:5], 0xb0
	s_load_dwordx2 s[34:35], s[4:5], 0xf0
	s_load_dwordx8 s[16:23], s[4:5], 0xd0
	s_mov_b32 s33, s81
	v_readlane_b32 s58, v255, 0
	s_mov_b32 s2, s83
	v_readlane_b32 s59, v255, 3
	s_lshl_b32 s2, s58, 3
	s_add_i32 s36, s2, s59
	s_lshl_b32 s38, s33, 3
	s_add_i32 s44, s79, 1
	s_cmp_lg_u32 s79, 3
	s_cselect_b64 s[48:49], -1, 0
	s_cmp_lt_i32 s36, 0x8000
	s_cselect_b64 s[2:3], -1, 0
	v_lshl_add_u32 v48, s59, 6, v249
	v_cndmask_b32_e64 v0, 0, 1, s[2:3]
	s_cmp_eq_u32 s79, 3
	v_and_b32_e32 v110, 63, v48
	s_and_b64 s[50:51], s[48:49], exec
	s_cbranch_scc0 .Lf3_s1_done
	s_and_b32 s2, s58, 1
	s_cbranch_scc0 .Lf3_s1_done
	v_readlane_b32 s3, v255, 59
	s_cmp_lg_u32 s3, 0
	s_cbranch_scc1 .Lf3_s1_done
	s_mov_b32 s3, 1
	v_writelane_b32 v255, s3, 59
	v_lshlrev_b32_e32 v50, 2, v48
	s_waitcnt lgkmcnt(0)
	s_branch .LBB0_1617
.Lf3_s1_done:
	s_cmp_eq_u32 s79, 3
	s_mov_b64 s[50:51], -1
	v_cmp_ne_u32_e64 s[2:3], 1, v0
	s_cbranch_scc1 .LBB0_1590
	s_and_b64 vcc, exec, s[2:3]
	s_cbranch_vccnz .LBB0_1589
	v_readlane_b32 s50, v255, 15
	v_readlane_b32 s51, v255, 16
	s_lshl_b64 s[50:51], s[50:51], 2
	s_load_dwordx2 s[4:5], s[4:5], 0x20
	s_waitcnt lgkmcnt(0)
	s_add_u32 s50, s16, s50
	s_addc_u32 s51, s17, s51
	s_ashr_i32 s39, s38, 31
	s_cmp_lg_u64 s[22:23], 0
	s_cselect_b64 s[52:53], -1, 0
	s_lshl_b32 s54, s44, 10
	s_mov_b32 s55, s45
	s_lshl_b64 s[54:55], s[54:55], 2
	s_add_u32 s4, s4, s54
	s_addc_u32 s5, s5, s55
	s_lshl_b32 s54, s33, 5
	v_lshlrev_b32_e32 v176, 4, v110
	s_ashr_i32 s37, s36, 31
	s_ashr_i32 s55, s54, 31
	v_lshl_add_u64 v[6:7], s[4:5], 0, v[176:177]
	s_lshl_b64 s[4:5], s[36:37], 11
	v_lshlrev_b32_e32 v0, 3, v48
	s_lshl_b64 s[56:57], s[54:55], 11
	s_lshl_b64 s[60:61], s[38:39], 12
	v_and_b32_e32 v2, 0x1f8, v0
	s_add_u32 s42, s60, s4
	v_or_b32_e32 v0, s4, v2
	v_mov_b32_e32 v1, s5
	s_addc_u32 s55, s61, s5
	v_lshl_add_u64 v[8:9], s[34:35], 0, v[0:1]
	v_lshl_add_u64 v[10:11], s[22:23], 0, v[0:1]
	v_mov_b32_e32 v1, s55
	s_mul_i32 s55, s38, 0x1800
	v_or_b32_e32 v0, s42, v2
	s_mul_hi_i32 s42, s38, 0x1800
	s_add_u32 s4, s55, s4
	s_addc_u32 s5, s42, s5
	v_lshl_add_u64 v[12:13], s[34:35], 0, v[0:1]
	v_lshl_add_u64 v[14:15], s[22:23], 0, v[0:1]
	v_or_b32_e32 v0, s4, v2
	s_add_u32 s4, s38, s36
	v_mov_b32_e32 v1, s5
	s_addc_u32 s5, s39, s37
	s_lshl_b64 s[4:5], s[4:5], 11
	v_or_b32_e32 v2, s4, v2
	v_mov_b32_e32 v3, s5
	v_lshl_add_u64 v[4:5], s[50:51], 0, v[176:177]
	s_mov_b64 s[50:51], 0
	v_lshl_add_u64 v[16:17], s[34:35], 0, v[0:1]
	v_lshl_add_u64 v[18:19], s[34:35], 0, v[2:3]
	v_lshl_add_u64 v[20:21], s[22:23], 0, v[0:1]
	v_lshl_add_u64 v[22:23], s[22:23], 0, v[2:3]
	s_mov_b32 s37, s36
	s_branch .LBB0_1587

; __global__ void __launch_bounds__(512, 2) mega(Args args) {
;     ...
;             if (more) { convert_weights(in, l + 1, ws, lds, gw, NGW, wave, lane); filter_gen(in, l + 1, ws, lds, vcu, G, wave, tid); }
.LBB0_1617:
	v_readlane_b32 s2, v255, 59
	s_cmp_eq_u32 s2, 2
	s_cbranch_scc0 .Lf3_s3_done
	s_mov_b32 s2, 0
	v_writelane_b32 v255, s2, 59
	s_branch .LBB0_1671

; #define PH_END } ++ph; if (ph > lo && ph < hi) { if (ph == 1) grid.sync(); else { KArgsP kq_ = (KArgsP)__builtin_amdgcn_kernarg_segment_ptr(); asm volatile("" : "+s"(kq_)); \
;         xcd_barrier((unsigned*)LOAD_ARGS(kq_).ws, (volatile LAS unsigned*)(lds + LDS_ST), opaque_tid(wave0) == 0, (unsigned)G0); } }
; __global__ void __launch_bounds__(512, 2) mega(Args args) {
;     ...
;             if (more) { convert_weights(in, l + 1, ws, lds, gw, NGW, wave, lane); filter_gen(in, l + 1, ws, lds, vcu, G, wave, tid); }
;         PH_END
.LBB0_1670:
	s_barrier
	v_readlane_b32 s2, v255, 59
	s_cmp_eq_u32 s2, 1
	s_cbranch_scc0 .Lf3_s2_done
	s_mov_b32 s2, 2
	v_writelane_b32 v255, s2, 59
	s_branch .Lf3_pro
.Lf3_s2_done:
.LBB0_1671:
	s_add_i32 s75, s75, 22
	v_readlane_b32 s4, v255, 1
	v_readlane_b32 s5, v255, 2
	s_cmp_gt_i32 s75, s4
	s_cselect_b64 s[2:3], -1, 0
	s_cmp_lt_i32 s75, s5
	s_cselect_b64 s[4:5], -1, 0
	s_and_b64 s[2:3], s[2:3], s[4:5]
	s_andn2_b64 vcc, exec, s[2:3]
	s_cbranch_vccz .LBB0_1672
	s_getpc_b64 s[98:99]
